# prologue in two stages: only layer-0 needs before the first barrier, weight tiles of layers 1-3 converted afterwards by odd-blockIdx workgroups (completion counter + release/acquire before in-proj of
# speedup vs baseline: 1.0051x; 1.0051x over previous
; #define LAS __attribute__((address_space(3)))
; __global__ void __launch_bounds__(NTHREADS, 2) mega(Params p_, int ph_lo, int ph_hi) {
;     const Params& p = *(const Params*)__builtin_amdgcn_kernarg_segment_ptr();
;     extern __shared__ __attribute__((aligned(16))) char smem[];
;     cg::grid_group grid = cg::this_grid();
;     __shared__ uint4 xb_words;
;     if (threadIdx.x == 0) xb_words = make_uint4(0u, 0u, 0u, 0u);
;     __syncthreads();
;     XcdBarrier xb = xcd_barrier_post(p.bar, (volatile LAS unsigned*)&xb_words);
;     for (int ph = ph_lo; ph < ph_hi; ++ph) {
.LBB0_5:
	s_or_b64 exec, exec, s[4:5]
	s_load_dwordx2 s[52:53], s[0:1], 0x110
	s_waitcnt lgkmcnt(0)
	s_cmp_ge_i32 s52, s53
	s_cbranch_scc1 .LBB0_416
	v_writelane_b32 v255, 0, 43
	s_cmpk_lg_i32 s66, 0x200
	s_cselect_b64 s[4:5], -1, 0
	v_writelane_b32 v254, s4, 3
	s_mul_i32 s7, s67, s66
	s_mov_b32 s75, 0
	v_writelane_b32 v254, s5, 4
	s_mov_b32 s15, s75
	v_readlane_b32 s13, v254, 0
	s_and_b32 s14, s13, 7
	s_lshr_b32 s8, s13, 3
	s_cmpk_lt_i32 s13, 0x480
	s_cselect_b64 s[4:5], -1, 0
	v_writelane_b32 v254, s4, 5
	s_mul_i32 s16, s14, 0x900
	s_mul_hi_u32 s12, s8, 0x1c71c71d
	v_writelane_b32 v254, s5, 6
	s_add_u32 s4, s0, 0xb0
	s_addc_u32 s5, s1, 0
	v_writelane_b32 v254, s4, 7
	s_mul_i32 s12, s12, 9
	s_mul_i32 s11, s14, 9
	v_writelane_b32 v254, s5, 8
	s_add_u32 s4, s0, 0xa8
	s_addc_u32 s5, s1, 0
	v_writelane_b32 v254, s4, 9
	s_mov_b32 s19, s75
	v_lshrrev_b32_e32 v1, 20, v0
	v_writelane_b32 v254, s5, 10
	s_add_u32 s4, s0, 16
	s_addc_u32 s5, s1, 0
	v_writelane_b32 v254, s4, 11
	s_lshl_b32 s2, s8, 4
	v_lshrrev_b32_e32 v0, 10, v0
	v_writelane_b32 v254, s5, 12
	v_writelane_b32 v254, s2, 13
	s_lshl_b32 s2, s13, 4
	s_and_b32 s6, s2, 0x380
	s_lshl_b32 s2, s6, 6
	s_cmpk_lt_u32 s13, 0x100
	v_writelane_b32 v254, s2, 14
	s_cselect_b64 s[4:5], -1, 0
	v_writelane_b32 v254, s4, 15
	s_and_b32 s2, s13, 0x80
	s_lshl_b32 s18, s14, 20
	v_writelane_b32 v254, s5, 16
	s_lshl_b32 s4, s13, 3
	s_and_b32 s5, s4, 64
	s_or_b32 s9, s2, s5
	s_and_b32 s2, s4, 0x380
	s_or_b32 s5, s9, 0x800
	s_lshl_b32 s4, s2, 6
	v_writelane_b32 v254, s4, 17
	s_add_i32 s4, s5, s16
	s_lshl_b32 s10, s4, 5
	s_lshl_b32 s20, s14, 23
	s_cmpk_gt_u32 s13, 0x1f7
	v_writelane_b32 v254, s5, 18
	s_cselect_b64 s[4:5], -1, 0
	s_sub_i32 s8, s8, s12
	s_add_i32 s8, s11, s8
	v_writelane_b32 v254, s8, 19
	s_mul_i32 s8, s13, 0xe38f
	s_lshr_b32 s8, s8, 22
	v_writelane_b32 v254, s8, 20
	s_lshl_b32 s8, s13, 2
	v_writelane_b32 v254, s8, 21
	s_lshl_b32 s8, s66, 2
	s_cmpk_lt_i32 s13, 0x1380
	v_writelane_b32 v254, s8, 22
	s_cselect_b64 s[22:23], -1, 0
	v_writelane_b32 v254, s22, 23
	s_lshl_b32 s8, s13, 8
	s_lshl_b32 s79, s66, 8
	v_writelane_b32 v254, s23, 24
	v_writelane_b32 v254, s8, 25
	s_cmp_eq_u32 s13, 0
	s_load_dword s8, s[0:1], 0x120
	s_cselect_b64 s[12:13], -1, 0
	v_writelane_b32 v254, s12, 26
	s_cmp_lt_i32 s53, 18
	v_or_b32_e32 v0, v0, v1
	v_writelane_b32 v254, s13, 27
	s_cselect_b64 s[12:13], -1, 0
	v_writelane_b32 v254, s12, 28
	s_waitcnt lgkmcnt(0)
; #define LAS __attribute__((address_space(3)))
; DI unsigned xb_ld(unsigned* p)              { return __hip_atomic_load(p, __ATOMIC_RELAXED, __HIP_MEMORY_SCOPE_AGENT); }
; DI unsigned xb_add(unsigned* p, unsigned v) { return __hip_atomic_fetch_add(p, v, __ATOMIC_RELAXED, __HIP_MEMORY_SCOPE_AGENT); }
; DI XcdBarrier xcd_barrier_post(unsigned* bar, volatile LAS unsigned* st) {
;     XcdBarrier b; b.bar = bar; b.x = xb_xcc_id(); b.st = st;
;     if (threadIdx.x == 0) (void)xb_add(&bar[XB_XCNT(b.x)], 1u);
;     return b;
; }
; DI void xcd_barrier_complete(unsigned* bar, unsigned x, unsigned& nloc, unsigned& nx) {
;     const unsigned G = gridDim.x * gridDim.y * gridDim.z;
;     unsigned sum, cnt, mine, sp = 0u;
;     for (;;) {
;         sum = 0u; cnt = 0u; mine = 0u;
; #pragma unroll
;         for (unsigned j = 0; j < 16; ++j) { const unsigned c = xb_ld(&bar[XB_XCNT(j)]); sum += c; cnt += (c > 0u) ? 1u : 0u; mine = (j == x) ? c : mine; }
;         if (sum == G) break;
;         __builtin_amdgcn_s_sleep(1);
;         if ((++sp & 255u) == 0u) { if (xb_ld(&bar[XB_TMO])) break; if (sp > XB_SPIN_CAP) { atomicAdd(&bar[XB_TMO], 1u); break; } }
;     }
;     nloc = mine > 0u ? mine : 1u; nx = cnt > 0u ? cnt : 1u;
; }
; DI void xcd_barrier(const XcdBarrier& b) {
;     asm volatile("s_waitcnt vmcnt(0)" ::: "memory");
;     __syncthreads();
;     if (threadIdx.x == 0) {
;         unsigned* bar = b.bar;
;         __builtin_amdgcn_s_waitcnt(0);
;         unsigned nloc = b.st[0], nx = b.st[1];
;         if (nloc == 0u) { xcd_barrier_complete(bar, b.x, nloc, nx); b.st[0] = nloc; b.st[1] = nx; }
;         const unsigned old = xb_add(&bar[XB_XSUB(b.x)], 1u);
;         const unsigned gen = old / nloc;
;         if (old + 1u == (gen + 1u) * nloc) {
;             __builtin_amdgcn_fence(__ATOMIC_RELEASE, "agent");
;             asm volatile("s_waitcnt vmcnt(0)" ::: "memory");
;             const unsigned og = xb_add(&bar[XB_TOP], 1u);
;             const unsigned tg = og / nx;
;             if (og + 1u == (tg + 1u) * nx) xb_add(&bar[XB_TOPGEN], 1u);
;             else XB_SPIN(xb_ld(&bar[XB_TOPGEN]) == tg, bar);
;             __builtin_amdgcn_fence(__ATOMIC_ACQUIRE, "agent");
;             xb_add(&bar[XB_XGEN(b.x)], 1u);
;             asm volatile("s_waitcnt vmcnt(0)" ::: "memory");
;         } else {
;             XB_SPIN(xb_ld(&bar[XB_XGEN(b.x)]) == gen, bar);
	s_mul_i32 s7, s7, s8
	s_mov_b32 s21, s75
	v_writelane_b32 v254, s13, 29
	s_add_u32 s12, s68, 0x200
	v_writelane_b32 v254, s7, 30
	s_addc_u32 s13, s69, 0
	v_writelane_b32 v254, s12, 31
	v_mov_b32_e32 v193, 0
	v_mbcnt_lo_u32_b32 v1, -1, 0
	v_writelane_b32 v254, s13, 32
	s_add_u32 s12, s68, 0x1000
	s_addc_u32 s13, s69, 0
	v_writelane_b32 v254, s12, 33
	v_mov_b32_e32 v201, 0x358637bd
	v_mov_b32_e32 v202, 0x3c0881c4
	v_writelane_b32 v254, s13, 34
	s_add_u32 s12, s68, 0x1100
	s_addc_u32 s13, s69, 0
	v_writelane_b32 v254, s12, 35
	v_mov_b32_e32 v203, 0xbab64f3b
	v_mov_b32_e32 v204, 0x7c
	v_writelane_b32 v254, s13, 36
	s_add_u32 s12, s68, 0x1200
	s_addc_u32 s13, s69, 0
	v_writelane_b32 v254, s12, 37
	v_mbcnt_hi_u32_b32 v205, -1, v1
	v_mov_b32_e32 v206, 0x3e38aa3b
	v_writelane_b32 v254, s13, 38
	s_add_u32 s12, s68, 0x1300
	s_addc_u32 s13, s69, 0
	v_writelane_b32 v254, s12, 39
	s_cmp_eq_u32 s3, 15
	v_mov_b32_e32 v207, 0x3e8293ee
	v_writelane_b32 v254, s13, 40
	s_cselect_b64 s[12:13], -1, 0
	v_writelane_b32 v254, s12, 41
	s_cmp_eq_u32 s3, 14
	v_mov_b32_e32 v208, 0x70
	v_writelane_b32 v254, s13, 42
	s_cselect_b64 s[12:13], -1, 0
	v_writelane_b32 v254, s12, 43
	s_cmp_eq_u32 s3, 13
	v_mov_b32_e32 v209, 0x7f800000
	v_writelane_b32 v254, s13, 44
	s_cselect_b64 s[12:13], -1, 0
	v_writelane_b32 v254, s12, 45
	s_cmp_eq_u32 s3, 12
	v_not_b32_e32 v211, 63
	v_writelane_b32 v254, s13, 46
	s_cselect_b64 s[12:13], -1, 0
	v_writelane_b32 v254, s12, 47
	s_cmp_eq_u32 s3, 11
	v_not_b32_e32 v212, 31
	v_writelane_b32 v254, s13, 48
	s_cselect_b64 s[12:13], -1, 0
	v_writelane_b32 v254, s12, 49
	s_cmp_eq_u32 s3, 10
	v_mov_b32_e32 v213, 0x7fc00000
	v_writelane_b32 v254, s13, 50
	s_cselect_b64 s[12:13], -1, 0
	v_writelane_b32 v254, s12, 51
	s_cmp_eq_u32 s3, 9
	s_movk_i32 s61, 0x800
	v_writelane_b32 v254, s13, 52
	s_cselect_b64 s[12:13], -1, 0
	v_writelane_b32 v254, s12, 53
	s_cmp_eq_u32 s3, 8
	s_movk_i32 s78, 0x2000
	v_writelane_b32 v254, s13, 54
	s_cselect_b64 s[12:13], -1, 0
	v_writelane_b32 v254, s12, 55
	s_cmp_eq_u32 s3, 7
	s_brev_b32 s86, 1
	v_writelane_b32 v254, s13, 56
	s_cselect_b64 s[12:13], -1, 0
	v_writelane_b32 v254, s12, 57
	s_cmp_eq_u32 s3, 6
	s_mov_b32 s87, 0x800000
	v_writelane_b32 v254, s13, 58
	s_cselect_b64 s[12:13], -1, 0
	v_writelane_b32 v254, s12, 59
	s_cmp_eq_u32 s3, 5
	s_mov_b32 s37, 0xbfb8aa3b
	v_writelane_b32 v254, s13, 60
	s_cselect_b64 s[12:13], -1, 0
	v_writelane_b32 v254, s12, 61
	s_cmp_eq_u32 s3, 4
	s_movk_i32 s33, 0x104
	v_writelane_b32 v254, s13, 62
	s_cselect_b64 s[12:13], -1, 0
	v_writelane_b32 v254, s12, 63
	s_cmp_eq_u32 s3, 3
	s_mov_b32 s31, 0x42ce8ed0
	v_writelane_b32 v255, s13, 0
	s_cselect_b64 s[12:13], -1, 0
	v_writelane_b32 v255, s12, 1
	s_cmp_eq_u32 s3, 2
	s_mov_b32 s67, 0xc2b17218
	v_writelane_b32 v255, s13, 2
	s_cselect_b64 s[12:13], -1, 0
	v_writelane_b32 v255, s12, 3
	s_cmp_eq_u32 s3, 1
	s_mov_b32 s83, 0x3c439041
	v_writelane_b32 v255, s13, 4
	s_cselect_b64 s[12:13], -1, 0
	v_writelane_b32 v255, s12, 5
	s_cmp_eq_u32 s3, 0
	s_mov_b32 s36, 0xdb629599
	v_writelane_b32 v255, s13, 6
	s_cselect_b64 s[12:13], -1, 0
	s_lshl_b32 s3, s3, 8
	s_add_u32 s3, s68, s3
	v_writelane_b32 v255, s12, 7
	s_addc_u32 s7, s69, 0
	s_mov_b32 s30, 0xf534ddc0
	v_writelane_b32 v255, s13, 8
	s_add_u32 s12, s3, 0x1400
	s_addc_u32 s13, s7, 0
	v_writelane_b32 v255, s12, 9
	s_mov_b32 s70, 0xfc2757d1
	s_mov_b32 s71, 0x4e441529
	v_writelane_b32 v255, s13, 10
	s_add_u32 s12, s3, 0x2400
	s_addc_u32 s13, s7, 0
	v_writelane_b32 v255, s12, 11
	s_movk_i32 s3, 0x3ff
	v_and_or_b32 v0, v0, s3, v200
	v_writelane_b32 v255, s13, 12
	s_add_u32 s12, s68, 0x3400
	s_addc_u32 s13, s69, 0
	v_writelane_b32 v255, s12, 13
	s_mov_b32 s72, 0xa2f9836e
	s_mov_b32 s73, 0x3fc90fda
	v_writelane_b32 v255, s13, 14
	s_add_u32 s12, s68, 0x3500
	s_addc_u32 s13, s69, 0
	v_writelane_b32 v255, s12, 15
	s_or_b32 s3, s9, s16
	s_lshl_b32 s3, s3, 6
	v_writelane_b32 v255, s13, 16
	v_writelane_b32 v255, s14, 17
	s_add_i32 s3, s3, 0x20000
	s_xor_b64 s[4:5], s[4:5], -1
	v_writelane_b32 v255, s15, 18
	v_writelane_b32 v255, s18, 19
	s_lshl_b32 s2, s2, 2
	s_lshl_b32 s74, s6, 2
	v_writelane_b32 v255, s19, 20
	v_writelane_b32 v255, s20, 21
	s_mov_b32 s18, 0x3f22f983
	s_mov_b32 s19, 0xbfc90fda
	v_writelane_b32 v255, s21, 22
	v_writelane_b32 v255, s16, 23
	v_writelane_b32 v255, s3, 24
	s_lshl_b32 s3, s10, 1
	v_writelane_b32 v255, s3, 25
	v_writelane_b32 v255, s4, 26
	s_lshl_b32 s3, s66, 3
	s_movk_i32 s20, 0x3000
	v_writelane_b32 v255, s5, 27
	v_writelane_b32 v255, s3, 28
	s_add_i32 s3, 32, 0x11000
	v_writelane_b32 v255, s3, 29
	v_writelane_b32 v255, s2, 30
	v_cmp_eq_u32_e64 s[4:5], 0, v0
	s_movk_i32 s21, 0x7ff
	v_writelane_b32 v255, s3, 31
	v_writelane_b32 v255, s4, 32
	s_brev_b32 s3, 18
	s_mov_b32 s2, 0xfe5163ab
	s_movk_i32 s82, 0x1f8
	s_mov_b64 s[26:27], 0x1000
	v_writelane_b32 v255, s5, 33
	s_mov_b64 s[76:77], 0x20000
	s_mov_b64 s[84:85], 0x240000
	s_mov_b64 s[14:15], 0x21000
	s_mov_b64 s[22:23], 0x241000
	s_mov_b64 s[10:11], 0x30000
	s_mov_b64 s[24:25], 0x360000
	s_mov_b64 s[38:39], 0x31000
	s_mov_b64 s[64:65], 0x361000
	s_mov_b64 s[16:17], 0x2000
	s_mov_b64 s[90:91], 0x3000
	s_mov_b64 s[92:93], 0x4000
	s_mov_b64 s[94:95], 0x5000
	s_mov_b64 s[80:81], 0x70000
	s_mov_b64 s[96:97], 0x71000
	s_mov_b64 s[12:13], 0x242000
	s_mov_b64 s[88:89], 0x243000
	s_branch .LBB0_11

; DI int otid() { int t = threadIdx.x; asm volatile("" : "+v"(t)); return t; }
; DI void prologue_phase(const Params& p, char* smem) {
;     const int nb = gridDim.x, bid = blockIdx.x, tid = otid();
;     constexpr int N_ADA = DEPTH * 96, N_TIN = DEPTH * 16 * 56, N_TOUT = DEPTH * 16 * 16;
;     for (int it = bid; it < N_ADA + N_TIN + N_TOUT; it += nb) {
;         if (it < N_ADA) adaln_item(p, it, smem);
;         else if (it < N_ADA + N_TIN) {
;             const int j = it - N_ADA, l = j / (16 * 56), r = j % (16 * 56), kt = r / 56, nt = r % 56;
;             transpose_item(p.w_in + (size_t)l * D * INW, p.wtin + (size_t)l * INW * D, D, INW, kt, nt, smem);
;         } else {
;             const int j = it - N_ADA - N_TIN, l = j / 256, r = j % 256, kt = r / 16, nt = r % 16;
;             transpose_item(p.w_out + (size_t)l * D * D, p.wtout + (size_t)l * D * D, D, D, kt, nt, smem);
;         }
;     }
.LBB0_137:
	s_andn2_b64 vcc, exec, s[4:5]
	s_cbranch_vccnz .LBB0_292
	s_cmp_eq_u32 s98, 1
	s_mov_b64 s[4:5], -1
	s_cbranch_scc1 .LBB0_183
	s_cmp_lg_u32 s60, 0
	s_cbranch_scc1 .Lpro2_skip
	v_readlane_b32 s4, v254, 0
	s_nop 0
	s_bitcmp1_b32 s4, 0
	s_cbranch_scc0 .Lpro2_skip
	s_lshr_b32 s100, s4, 1
	v_writelane_b32 v255, 1, 43
.Lpro2_next:
	s_cmpk_ge_i32 s100, 0xd80
	s_cbranch_scc1 .Lpro2_done
	s_movk_i32 s42, 0x600
	s_cmpk_lt_i32 s100, 0xa80
	s_cselect_b32 s42, 0x500, s42
	s_add_i32 s42, s42, s100
	s_branch .Lpro_body
.Lpro2_step:
	s_addk_i32 s100, 0x100
	s_waitcnt lgkmcnt(0)
	s_branch .Lpro2_next
.Lpro2_done:
	v_writelane_b32 v255, 0, 43
	s_waitcnt vmcnt(0)
	s_barrier
	s_and_saveexec_b64 s[4:5], s[54:55]
	s_cbranch_execz .Lpro2_reld
	buffer_wbl2 sc1
	s_waitcnt vmcnt(0)
	v_mov_b32_e32 v0, 0x3440
	v_mov_b32_e32 v1, 1
	global_atomic_add v0, v1, s[68:69]
.Lpro2_reld:
	s_or_b64 exec, exec, s[4:5]
.Lpro2_skip:
	v_mov_b32_e32 v16, v200
	v_readlane_b32 s4, v254, 21
	v_readlane_b32 s100, v254, 22
	s_mov_b32 s101, 0x47ff
	s_cmp_lg_u32 s100, 0x800
	s_cbranch_scc1 .Lnorm_nomap
	s_lshr_b32 s100, s4, 5
	s_lshl_b32 s100, s100, 2
	s_bfe_u32 s4, s4, 0x30002
	s_mulk_i32 s4, 0x900
	s_add_i32 s101, s4, 0x8ff
	s_add_i32 s4, s4, s100
	s_movk_i32 s100, 0x100

; DI void inproj_phase(const Params& p, int l, char* smem) {
;     constexpr int NT = 28, MT = NTOK / 256;
;     const bool xmap = gridDim.x == 512;
;     const int xcd = blockIdx.x & 7, xj = blockIdx.x >> 3;
;     for (int it = 0;; ++it) {
;         int mtile, nt;
;         if (xmap) {
;             if (it >= 4 || xj >= 63) break;
;             mtile = 9 * xcd + (xj % 9); nt = 7 * it + (xj / 9);
;         } else {
;             const int tile = blockIdx.x + it * gridDim.x;
;             if (tile >= MT * NT) break;
;             mtile = tile / NT; nt = tile % NT;
;         }
;         const int n0 = nt * 128;
;         const bf16_t* W = p.wtin + (size_t)l * INW * D + (size_t)n0 * 32;
;         const bf16_t* X = p.hmix + (size_t)mtile * 256 * 32;
.LBB0_183:
	s_andn2_b64 vcc, exec, s[4:5]
	s_cbranch_vccnz .LBB0_292
	s_cmp_eq_u32 s60, 0
	s_cbranch_scc1 .Lpro2_ok
	s_and_saveexec_b64 s[4:5], s[54:55]
	s_cbranch_execz .Lpro2_acqd
	v_mov_b32_e32 v0, 0x3440
.Lpro2_poll:
	global_load_dword v1, v0, s[68:69] sc1
	s_waitcnt vmcnt(0)
	v_cmp_gt_u32_e32 vcc, 0x100, v1
	s_cbranch_vccz .Lpro2_have
	s_sleep 2
	s_branch .Lpro2_poll
.Lpro2_have:
	buffer_inv sc1
	s_waitcnt vmcnt(0)

; DI void inproj_phase(const Params& p, int l, char* smem) {
;     constexpr int NT = 28, MT = NTOK / 256;
;     const bool xmap = gridDim.x == 512;
;     const int xcd = blockIdx.x & 7, xj = blockIdx.x >> 3;
;     for (int it = 0;; ++it) {
;         int mtile, nt;
.Lpro2_ok:
	s_lshl_b32 s4, s60, 6
	s_ashr_i32 s5, s4, 31
	v_writelane_b32 v255, s4, 36
	s_lshl_b32 s48, s60, 5
	s_mul_hi_i32 s62, s60, 0x700000
	s_mul_i32 s63, s60, 0x700000
	v_writelane_b32 v255, s5, 37
	s_ashr_i32 s49, s48, 31
	s_mov_b32 s98, 0
	s_branch .LBB0_187

; DI void prologue_phase(const Params& p, char* smem) {
;     ...
;     for (int it = bid; it < N_ADA + N_TIN + N_TOUT; it += nb) {
;         if (it < N_ADA) adaln_item(p, it, smem);
;         else if (it < N_ADA + N_TIN) {
;             const int j = it - N_ADA, l = j / (16 * 56), r = j % (16 * 56), kt = r / 56, nt = r % 56;
;             transpose_item(p.w_in + (size_t)l * D * INW, p.wtin + (size_t)l * INW * D, D, INW, kt, nt, smem);
;         } else {
;             const int j = it - N_ADA - N_TIN, l = j / 256, r = j % 256, kt = r / 16, nt = r % 16;
;             transpose_item(p.w_out + (size_t)l * D * D, p.wtout + (size_t)l * D * D, D, D, kt, nt, smem);
;         }
;     }
.LBB0_297:
	v_readlane_b32 s4, v255, 43
	s_nop 0
	s_cmp_lg_u32 s4, 0
	s_cbranch_scc1 .Lpro2_step
	s_add_i32 s42, s42, s66
	s_cmpk_gt_i32 s42, 0x137f
	s_waitcnt lgkmcnt(0)
	s_cbranch_scc1 .LBB0_319
.LBB0_298:
	s_cmpk_lt_i32 s42, 0x500
	s_cbranch_scc1 .Lpro_body
	s_cmpk_lt_i32 s42, 0xf80
	s_cbranch_scc1 .LBB0_297
	s_cmpk_lt_i32 s42, 0x1080
	s_cbranch_scc1 .Lpro_body
	s_branch .LBB0_297
